# v40 + odd workgroups run the pool-operand phase before the prologue (latency-bound weight copies beside the bandwidth-bound x stream)
# baseline (speedup 1.0000x reference)
.LBB0_16:
	v_writelane_b32 v251, s95, 48
	s_andn2_b64 vcc, exec, s[0:1]
	v_writelane_b32 v251, s97, 49
	s_cbranch_vccnz .LBB0_538
	s_bitcmp1_b32 s95, 0
	s_cbranch_scc0 .Lalt_p0first
	s_and_b32 s85, s54, 0xffffffc0
	s_lshl_b32 s96, s97, 9
	s_branch .LBB0_538
.Lalt_p0first:
	v_readlane_b32 s2, v251, 2
	v_readlane_b32 s3, v251, 3
	v_mov_b32 v1, 0
	s_and_b32 s85, s54, 0xffffffc0
	v_mbcnt_lo_u32_b32 v1, -1, v1
	v_mbcnt_hi_u32_b32 v2, -1, v1
	s_lshl_b32 s27, s95, 3
	s_lshl_b32 s4, s97, 3
	v_add_u32_e32 v3, s85, v2
	s_cmpk_eq_i32 s97, 0x100
	v_readfirstlane_b32 s29, v3
	s_cselect_b32 s11, 0x3f00, 0
	s_ashr_i32 s28, s29, 6
	s_mul_i32 s0, s28, 0x2100
	s_sub_i32 s5, 0x5600, s11
	s_lshl_b32 s96, s97, 9
	v_and_b32_e32 v1, 63, v2
	s_add_i32 s10, s0, 0
	s_add_i32 s26, s28, s27
	s_movk_i32 s13, 0x5600
	s_cmp_ge_i32 s26, s5
	v_lshrrev_b32_e32 v77, 4, v1
	v_lshlrev_b32_e32 v78, 2, v1
	v_and_b32_e32 v76, 7, v2
	v_lshrrev_b32_e32 v88, 3, v1
	s_mov_b32 s12, s26
	s_cbranch_scc1 .LBB0_84
	v_readlane_b32 s36, v251, 16
	v_mov_b32_e32 v2, 0
	v_readlane_b32 s44, v251, 24
	v_readlane_b32 s45, v251, 25
	v_lshlrev_b32_e32 v4, 4, v76
	v_mov_b32_e32 v5, v2
	s_cmp_lg_u64 s[44:45], 0
	v_lshl_add_u64 v[4:5], s[2:3], 0, v[4:5]
	s_mov_b64 s[0:1], 0x8c00000
	s_cselect_b64 s[6:7], -1, 0
	v_and_b32_e32 v79, 60, v78
	v_lshrrev_b32_e32 v81, 3, v1
	v_lshl_add_u64 v[70:71], v[4:5], 0, s[0:1]
	s_add_i32 s0, s11, s28
	v_lshl_add_u32 v3, v79, 2, s10
	v_mul_u32_u24_e32 v6, 0x104, v77
	v_mul_u32_u24_e32 v7, 0x410, v76
	v_lshlrev_b32_e32 v4, 2, v81
	s_add_i32 s0, s0, s27
	v_lshlrev_b32_e32 v80, 1, v77
	v_add3_u32 v82, s10, v7, v4
	v_or_b32_e32 v83, 8, v81
	v_or_b32_e32 v84, 16, v81
	v_or_b32_e32 v85, 24, v81
	v_or_b32_e32 v86, 32, v81
	v_or_b32_e32 v87, 40, v81
	v_or_b32_e32 v89, 48, v81
	v_or_b32_e32 v90, 56, v81
	s_lshl_b32 s14, s0, 6
	s_mov_b32 s15, 0x15800
	v_add_u32_e32 v91, v3, v6
	s_mov_b32 s12, s26
	v_readlane_b32 s37, v251, 17
	v_readlane_b32 s38, v251, 18
	v_readlane_b32 s39, v251, 19
	v_readlane_b32 s40, v251, 20
	v_readlane_b32 s41, v251, 21
	v_readlane_b32 s42, v251, 22
	v_readlane_b32 s43, v251, 23
	v_readlane_b32 s46, v251, 26
	v_readlane_b32 s47, v251, 27
	v_readlane_b32 s48, v251, 28
	v_readlane_b32 s49, v251, 29
	v_readlane_b32 s50, v251, 30
	v_readlane_b32 s51, v251, 31
	s_branch .LBB0_20

.LBB0_438:
	v_readlane_b32 s0, v251, 48
	s_nop 1
	s_bitcmp1_b32 s0, 0
	s_cbranch_scc1 .LBB0_631
	s_branch .LBB0_538
	s_waitcnt vmcnt(0)
	v_cmp_eq_u32_e32 vcc, 0, v0
	s_waitcnt lgkmcnt(0)
	s_barrier
	s_and_saveexec_b64 s[0:1], vcc
	s_cbranch_execz .LBB0_537
	v_mov_b32_e32 v1, s79
	s_waitcnt vmcnt(0) expcnt(0) lgkmcnt(0)
	ds_read_b32 v3, v1
	ds_read_b32 v1, v1 offset:4
	s_waitcnt lgkmcnt(1)
	v_cmp_ne_u32_e32 vcc, 0, v3
	s_cbranch_vccnz .LBB0_505
	v_readlane_b32 s2, v251, 0
	v_readlane_b32 s3, v251, 1
	s_load_dwordx2 s[4:5], s[2:3], 0x4
	v_readlane_b32 s6, v251, 2
	v_readlane_b32 s7, v251, 3
	s_add_u32 s2, s6, 0x4200
	s_addc_u32 s3, s7, 0
	s_lshl_b32 s10, s55, 8
	s_waitcnt lgkmcnt(0)
	s_mul_i32 s11, s4, s97
	s_add_u32 s12, s6, 0x4400
	s_mov_b32 s9, 0
	s_mul_i32 s11, s11, s5
	s_addc_u32 s13, s7, 0
	v_mov_b32_e32 v2, 0
	s_branch .LBB0_443

.Lp1f_w1_m1:
	v_mul_f32_e32 v144, s36, v144
	v_mul_f32_e32 v145, s36, v145
	v_mul_f32_e32 v146, s36, v146
	v_mul_f32_e32 v147, s36, v147
	v_mul_f32_e32 v148, s36, v148
	v_mul_f32_e32 v149, s36, v149
	v_mul_f32_e32 v150, s36, v150
	v_mul_f32_e32 v151, s36, v151
	v_pk_mul_f32 v[144:145], v[144:145], v[4:5]
	v_pk_mul_f32 v[146:147], v[146:147], v[6:7]
	v_pk_mul_f32 v[148:149], v[148:149], v[8:9]
	v_pk_mul_f32 v[150:151], v[150:151], v[10:11]
	v_mul_f32_e32 v152, s37, v152
	v_mul_f32_e32 v153, s37, v153
	v_mul_f32_e32 v154, s37, v154
	v_mul_f32_e32 v155, s37, v155
	v_mul_f32_e32 v156, s37, v156
	v_mul_f32_e32 v157, s37, v157
	v_mul_f32_e32 v158, s37, v158
	v_mul_f32_e32 v159, s37, v159
	v_pk_mul_f32 v[152:153], v[152:153], v[4:5]
	v_pk_mul_f32 v[154:155], v[154:155], v[6:7]
	v_pk_mul_f32 v[156:157], v[156:157], v[8:9]
	v_pk_mul_f32 v[158:159], v[158:159], v[10:11]
	v_mul_f32_e32 v160, s38, v160
	v_mul_f32_e32 v161, s38, v161
	v_mul_f32_e32 v162, s38, v162
	v_mul_f32_e32 v163, s38, v163
	v_mul_f32_e32 v164, s38, v164
	v_mul_f32_e32 v165, s38, v165
	v_mul_f32_e32 v166, s38, v166
	v_mul_f32_e32 v167, s38, v167
	v_pk_mul_f32 v[160:161], v[160:161], v[4:5]
	v_pk_mul_f32 v[162:163], v[162:163], v[6:7]
	v_pk_mul_f32 v[164:165], v[164:165], v[8:9]
	v_pk_mul_f32 v[166:167], v[166:167], v[10:11]
	v_mul_f32_e32 v168, s39, v168
	v_mul_f32_e32 v169, s39, v169
	v_mul_f32_e32 v170, s39, v170
	v_mul_f32_e32 v171, s39, v171
	v_mul_f32_e32 v172, s39, v172
	v_mul_f32_e32 v173, s39, v173
	v_mul_f32_e32 v174, s39, v174
	v_mul_f32_e32 v175, s39, v175
	v_pk_mul_f32 v[168:169], v[168:169], v[4:5]
	v_pk_mul_f32 v[170:171], v[170:171], v[6:7]
	v_pk_mul_f32 v[172:173], v[172:173], v[8:9]
	v_pk_mul_f32 v[174:175], v[174:175], v[10:11]
	v_mul_f32_e32 v176, s40, v176
	v_mul_f32_e32 v177, s40, v177
	v_mul_f32_e32 v178, s40, v178
	v_mul_f32_e32 v179, s40, v179
	v_mul_f32_e32 v180, s40, v180
	v_mul_f32_e32 v181, s40, v181
	v_mul_f32_e32 v182, s40, v182
	v_mul_f32_e32 v183, s40, v183
	v_pk_mul_f32 v[176:177], v[176:177], v[4:5]
	v_pk_mul_f32 v[178:179], v[178:179], v[6:7]
	v_pk_mul_f32 v[180:181], v[180:181], v[8:9]
	v_pk_mul_f32 v[182:183], v[182:183], v[10:11]
	v_mul_f32_e32 v184, s41, v184
	v_mul_f32_e32 v185, s41, v185
	v_mul_f32_e32 v186, s41, v186
	v_mul_f32_e32 v187, s41, v187
	v_mul_f32_e32 v188, s41, v188
	v_mul_f32_e32 v189, s41, v189
	v_mul_f32_e32 v190, s41, v190
	v_mul_f32_e32 v191, s41, v191
	v_pk_mul_f32 v[184:185], v[184:185], v[4:5]
	v_pk_mul_f32 v[186:187], v[186:187], v[6:7]
	v_pk_mul_f32 v[188:189], v[188:189], v[8:9]
	v_pk_mul_f32 v[190:191], v[190:191], v[10:11]
	v_mul_f32_e32 v192, s42, v192
	v_mul_f32_e32 v193, s42, v193
	v_mul_f32_e32 v194, s42, v194
	v_mul_f32_e32 v195, s42, v195
	v_mul_f32_e32 v196, s42, v196
	v_mul_f32_e32 v197, s42, v197
	v_mul_f32_e32 v198, s42, v198
	v_mul_f32_e32 v199, s42, v199
	v_pk_mul_f32 v[192:193], v[192:193], v[4:5]
	v_pk_mul_f32 v[194:195], v[194:195], v[6:7]
	v_pk_mul_f32 v[196:197], v[196:197], v[8:9]
	v_pk_mul_f32 v[198:199], v[198:199], v[10:11]
	v_mul_f32_e32 v200, s43, v200
	v_mul_f32_e32 v201, s43, v201
	v_mul_f32_e32 v202, s43, v202
	v_mul_f32_e32 v203, s43, v203
	v_mul_f32_e32 v204, s43, v204
	v_mul_f32_e32 v205, s43, v205
	v_mul_f32_e32 v206, s43, v206
	v_mul_f32_e32 v207, s43, v207
	v_pk_mul_f32 v[200:201], v[200:201], v[4:5]
	v_pk_mul_f32 v[202:203], v[202:203], v[6:7]
	v_pk_mul_f32 v[204:205], v[204:205], v[8:9]
	v_pk_mul_f32 v[206:207], v[206:207], v[10:11]
	v_pk_add_f32 v[208:209], v[208:209], v[80:81]
	v_pk_add_f32 v[210:211], v[210:211], v[82:83]
	v_pk_add_f32 v[212:213], v[212:213], v[84:85]
	v_pk_add_f32 v[214:215], v[214:215], v[86:87]
	v_pk_add_f32 v[208:209], v[208:209], v[144:145] neg_lo:[0,1] neg_hi:[0,1]
	v_pk_add_f32 v[210:211], v[210:211], v[146:147] neg_lo:[0,1] neg_hi:[0,1]
	v_pk_add_f32 v[212:213], v[212:213], v[148:149] neg_lo:[0,1] neg_hi:[0,1]
	v_pk_add_f32 v[214:215], v[214:215], v[150:151] neg_lo:[0,1] neg_hi:[0,1]
	v_fma_f32 v12, v208, s44, -v80
	v_fma_f32 v13, v209, s44, -v81
	v_fma_f32 v14, v210, s44, -v82
	v_fma_f32 v15, v211, s44, -v83
	v_fma_f32 v216, v212, s44, -v84
	v_fma_f32 v217, v213, s44, -v85
	v_fma_f32 v218, v214, s44, -v86
	v_fma_f32 v220, v215, s44, -v87
	v_cvt_pk_bf16_f32 v144, v12, v13
	v_cvt_pk_bf16_f32 v145, v14, v15
	v_cvt_pk_bf16_f32 v146, v216, v217
	v_cvt_pk_bf16_f32 v147, v218, v220
	s_add_i32 s52, s14, 0
	s_mov_b32 s53, 0
	s_lshl_b64 s[52:53], s[52:53], 13
	s_add_u32 s52, s52, s4
	s_addc_u32 s53, s53, s5
	global_store_dwordx2 v3, v[144:145], s[52:53]
	global_store_dwordx2 v3, v[146:147], s[52:53] offset:512
	v_pk_add_f32 v[208:209], v[208:209], v[88:89]
	v_pk_add_f32 v[210:211], v[210:211], v[90:91]
	v_pk_add_f32 v[212:213], v[212:213], v[92:93]
	v_pk_add_f32 v[214:215], v[214:215], v[94:95]
	v_pk_add_f32 v[208:209], v[208:209], v[152:153] neg_lo:[0,1] neg_hi:[0,1]
	v_pk_add_f32 v[210:211], v[210:211], v[154:155] neg_lo:[0,1] neg_hi:[0,1]
	v_pk_add_f32 v[212:213], v[212:213], v[156:157] neg_lo:[0,1] neg_hi:[0,1]
	v_pk_add_f32 v[214:215], v[214:215], v[158:159] neg_lo:[0,1] neg_hi:[0,1]
	v_fma_f32 v12, v208, s45, -v88
	v_fma_f32 v13, v209, s45, -v89
	v_fma_f32 v14, v210, s45, -v90
	v_fma_f32 v15, v211, s45, -v91
	v_fma_f32 v216, v212, s45, -v92
	v_fma_f32 v217, v213, s45, -v93
	v_fma_f32 v218, v214, s45, -v94
	v_fma_f32 v220, v215, s45, -v95
	v_cvt_pk_bf16_f32 v152, v12, v13
	v_cvt_pk_bf16_f32 v153, v14, v15
	v_cvt_pk_bf16_f32 v154, v216, v217
	v_cvt_pk_bf16_f32 v155, v218, v220
	s_add_i32 s52, s14, 1
	s_mov_b32 s53, 0
	s_lshl_b64 s[52:53], s[52:53], 13
	s_add_u32 s52, s52, s4
	s_addc_u32 s53, s53, s5
	global_store_dwordx2 v3, v[152:153], s[52:53]
	global_store_dwordx2 v3, v[154:155], s[52:53] offset:512
	v_pk_add_f32 v[208:209], v[208:209], v[96:97]
	v_pk_add_f32 v[210:211], v[210:211], v[98:99]
	v_pk_add_f32 v[212:213], v[212:213], v[100:101]
	v_pk_add_f32 v[214:215], v[214:215], v[102:103]
	v_pk_add_f32 v[208:209], v[208:209], v[160:161] neg_lo:[0,1] neg_hi:[0,1]
	v_pk_add_f32 v[210:211], v[210:211], v[162:163] neg_lo:[0,1] neg_hi:[0,1]
	v_pk_add_f32 v[212:213], v[212:213], v[164:165] neg_lo:[0,1] neg_hi:[0,1]
	v_pk_add_f32 v[214:215], v[214:215], v[166:167] neg_lo:[0,1] neg_hi:[0,1]
	v_fma_f32 v12, v208, s46, -v96
	v_fma_f32 v13, v209, s46, -v97
	v_fma_f32 v14, v210, s46, -v98
	v_fma_f32 v15, v211, s46, -v99
	v_fma_f32 v216, v212, s46, -v100
	v_fma_f32 v217, v213, s46, -v101
	v_fma_f32 v218, v214, s46, -v102
	v_fma_f32 v220, v215, s46, -v103
	v_cvt_pk_bf16_f32 v160, v12, v13
	v_cvt_pk_bf16_f32 v161, v14, v15
	v_cvt_pk_bf16_f32 v162, v216, v217
	v_cvt_pk_bf16_f32 v163, v218, v220
	s_add_i32 s52, s14, 2
	s_mov_b32 s53, 0
	s_lshl_b64 s[52:53], s[52:53], 13
	s_add_u32 s52, s52, s4
	s_addc_u32 s53, s53, s5
	global_store_dwordx2 v3, v[160:161], s[52:53]
	global_store_dwordx2 v3, v[162:163], s[52:53] offset:512
	v_pk_add_f32 v[208:209], v[208:209], v[104:105]
	v_pk_add_f32 v[210:211], v[210:211], v[106:107]
	v_pk_add_f32 v[212:213], v[212:213], v[108:109]
	v_pk_add_f32 v[214:215], v[214:215], v[110:111]
	v_pk_add_f32 v[208:209], v[208:209], v[168:169] neg_lo:[0,1] neg_hi:[0,1]
	v_pk_add_f32 v[210:211], v[210:211], v[170:171] neg_lo:[0,1] neg_hi:[0,1]
	v_pk_add_f32 v[212:213], v[212:213], v[172:173] neg_lo:[0,1] neg_hi:[0,1]
	v_pk_add_f32 v[214:215], v[214:215], v[174:175] neg_lo:[0,1] neg_hi:[0,1]
	v_fma_f32 v12, v208, s47, -v104
	v_fma_f32 v13, v209, s47, -v105
	v_fma_f32 v14, v210, s47, -v106
	v_fma_f32 v15, v211, s47, -v107
	v_fma_f32 v216, v212, s47, -v108
	v_fma_f32 v217, v213, s47, -v109
	v_fma_f32 v218, v214, s47, -v110
	v_fma_f32 v220, v215, s47, -v111
	v_cvt_pk_bf16_f32 v168, v12, v13
	v_cvt_pk_bf16_f32 v169, v14, v15
	v_cvt_pk_bf16_f32 v170, v216, v217
	v_cvt_pk_bf16_f32 v171, v218, v220
	s_add_i32 s52, s14, 3
	s_mov_b32 s53, 0
	s_lshl_b64 s[52:53], s[52:53], 13
	s_add_u32 s52, s52, s4
	s_addc_u32 s53, s53, s5
	global_store_dwordx2 v3, v[168:169], s[52:53]
	global_store_dwordx2 v3, v[170:171], s[52:53] offset:512
	v_pk_add_f32 v[208:209], v[208:209], v[112:113]
	v_pk_add_f32 v[210:211], v[210:211], v[114:115]
	v_pk_add_f32 v[212:213], v[212:213], v[116:117]
	v_pk_add_f32 v[214:215], v[214:215], v[118:119]
	v_pk_add_f32 v[208:209], v[208:209], v[176:177] neg_lo:[0,1] neg_hi:[0,1]
	v_pk_add_f32 v[210:211], v[210:211], v[178:179] neg_lo:[0,1] neg_hi:[0,1]
	v_pk_add_f32 v[212:213], v[212:213], v[180:181] neg_lo:[0,1] neg_hi:[0,1]
	v_pk_add_f32 v[214:215], v[214:215], v[182:183] neg_lo:[0,1] neg_hi:[0,1]
	v_fma_f32 v12, v208, s48, -v112
	v_fma_f32 v13, v209, s48, -v113
	v_fma_f32 v14, v210, s48, -v114
	v_fma_f32 v15, v211, s48, -v115
	v_fma_f32 v216, v212, s48, -v116
	v_fma_f32 v217, v213, s48, -v117
	v_fma_f32 v218, v214, s48, -v118
	v_fma_f32 v220, v215, s48, -v119
	v_cvt_pk_bf16_f32 v176, v12, v13
	v_cvt_pk_bf16_f32 v177, v14, v15
	v_cvt_pk_bf16_f32 v178, v216, v217
	v_cvt_pk_bf16_f32 v179, v218, v220
	s_add_i32 s52, s14, 4
	s_mov_b32 s53, 0
	s_lshl_b64 s[52:53], s[52:53], 13
	s_add_u32 s52, s52, s4
	s_addc_u32 s53, s53, s5
	global_store_dwordx2 v3, v[176:177], s[52:53]
	global_store_dwordx2 v3, v[178:179], s[52:53] offset:512
	v_pk_add_f32 v[208:209], v[208:209], v[120:121]
	v_pk_add_f32 v[210:211], v[210:211], v[122:123]
	v_pk_add_f32 v[212:213], v[212:213], v[124:125]
	v_pk_add_f32 v[214:215], v[214:215], v[126:127]
	v_pk_add_f32 v[208:209], v[208:209], v[184:185] neg_lo:[0,1] neg_hi:[0,1]
	v_pk_add_f32 v[210:211], v[210:211], v[186:187] neg_lo:[0,1] neg_hi:[0,1]
	v_pk_add_f32 v[212:213], v[212:213], v[188:189] neg_lo:[0,1] neg_hi:[0,1]
	v_pk_add_f32 v[214:215], v[214:215], v[190:191] neg_lo:[0,1] neg_hi:[0,1]
	v_fma_f32 v12, v208, s49, -v120
	v_fma_f32 v13, v209, s49, -v121
	v_fma_f32 v14, v210, s49, -v122
	v_fma_f32 v15, v211, s49, -v123
	v_fma_f32 v216, v212, s49, -v124
	v_fma_f32 v217, v213, s49, -v125
	v_fma_f32 v218, v214, s49, -v126
	v_fma_f32 v220, v215, s49, -v127
	v_cvt_pk_bf16_f32 v184, v12, v13
	v_cvt_pk_bf16_f32 v185, v14, v15
	v_cvt_pk_bf16_f32 v186, v216, v217
	v_cvt_pk_bf16_f32 v187, v218, v220
	s_add_i32 s52, s14, 5
	s_mov_b32 s53, 0
	s_lshl_b64 s[52:53], s[52:53], 13
	s_add_u32 s52, s52, s4
	s_addc_u32 s53, s53, s5
	global_store_dwordx2 v3, v[184:185], s[52:53]
	global_store_dwordx2 v3, v[186:187], s[52:53] offset:512
	v_pk_add_f32 v[208:209], v[208:209], v[128:129]
	v_pk_add_f32 v[210:211], v[210:211], v[130:131]
	v_pk_add_f32 v[212:213], v[212:213], v[132:133]
	v_pk_add_f32 v[214:215], v[214:215], v[134:135]
	v_pk_add_f32 v[208:209], v[208:209], v[192:193] neg_lo:[0,1] neg_hi:[0,1]
	v_pk_add_f32 v[210:211], v[210:211], v[194:195] neg_lo:[0,1] neg_hi:[0,1]
	v_pk_add_f32 v[212:213], v[212:213], v[196:197] neg_lo:[0,1] neg_hi:[0,1]
	v_pk_add_f32 v[214:215], v[214:215], v[198:199] neg_lo:[0,1] neg_hi:[0,1]
	v_fma_f32 v12, v208, s50, -v128
	v_fma_f32 v13, v209, s50, -v129
	v_fma_f32 v14, v210, s50, -v130
	v_fma_f32 v15, v211, s50, -v131
	v_fma_f32 v216, v212, s50, -v132
	v_fma_f32 v217, v213, s50, -v133
	v_fma_f32 v218, v214, s50, -v134
	v_fma_f32 v220, v215, s50, -v135
	v_cvt_pk_bf16_f32 v192, v12, v13
	v_cvt_pk_bf16_f32 v193, v14, v15
	v_cvt_pk_bf16_f32 v194, v216, v217
	v_cvt_pk_bf16_f32 v195, v218, v220
	s_add_i32 s52, s14, 6
	s_mov_b32 s53, 0
	s_lshl_b64 s[52:53], s[52:53], 13
	s_add_u32 s52, s52, s4
	s_addc_u32 s53, s53, s5
	global_store_dwordx2 v3, v[192:193], s[52:53]
	global_store_dwordx2 v3, v[194:195], s[52:53] offset:512
	v_pk_add_f32 v[208:209], v[208:209], v[136:137]
	v_pk_add_f32 v[210:211], v[210:211], v[138:139]
	v_pk_add_f32 v[212:213], v[212:213], v[140:141]
	v_pk_add_f32 v[214:215], v[214:215], v[142:143]
	v_pk_add_f32 v[208:209], v[208:209], v[200:201] neg_lo:[0,1] neg_hi:[0,1]
	v_pk_add_f32 v[210:211], v[210:211], v[202:203] neg_lo:[0,1] neg_hi:[0,1]
	v_pk_add_f32 v[212:213], v[212:213], v[204:205] neg_lo:[0,1] neg_hi:[0,1]
	v_pk_add_f32 v[214:215], v[214:215], v[206:207] neg_lo:[0,1] neg_hi:[0,1]
	v_fma_f32 v12, v208, s51, -v136
	v_fma_f32 v13, v209, s51, -v137
	v_fma_f32 v14, v210, s51, -v138
	v_fma_f32 v15, v211, s51, -v139
	v_fma_f32 v216, v212, s51, -v140
	v_fma_f32 v217, v213, s51, -v141
	v_fma_f32 v218, v214, s51, -v142
	v_fma_f32 v220, v215, s51, -v143
	v_cvt_pk_bf16_f32 v200, v12, v13
	v_cvt_pk_bf16_f32 v201, v14, v15
	v_cvt_pk_bf16_f32 v202, v216, v217
	v_cvt_pk_bf16_f32 v203, v218, v220
	s_add_i32 s52, s14, 7
	s_mov_b32 s53, 0
	s_lshl_b64 s[52:53], s[52:53], 13
	s_add_u32 s52, s52, s4
	s_addc_u32 s53, s53, s5
	global_store_dwordx2 v3, v[200:201], s[52:53]
	global_store_dwordx2 v3, v[202:203], s[52:53] offset:512
	s_add_i32 s13, s13, 1
	s_add_i32 s14, s14, 8
	s_add_i32 s15, s15, 8
	s_cmp_lt_u32 s13, 10
	s_cbranch_scc1 .Lp1f_loop
	v_readlane_b32 s95, v251, 48
	s_nop 1
	s_bitcmp1_b32 s95, 0
	s_cbranch_scc0 .Lalt_done
	v_readlane_b32 s52, v251, 52
	v_readlane_b32 s53, v251, 53
	v_readlane_b32 s54, v251, 59
	v_readlane_b32 s55, v251, 56
	v_readlane_b32 s56, v251, 57
	v_readlane_b32 s57, v251, 58
	v_readlane_b32 s97, v251, 49
	s_waitcnt lgkmcnt(0)
	s_barrier
	s_branch .Lalt_p0first
.Lalt_done:
.LBB0_631:
	v_readlane_b32 s0, v251, 63
	v_readlane_b32 s1, v252, 0
	s_or_b64 exec, exec, s[0:1]
	v_readlane_b32 s52, v251, 52
	v_readlane_b32 s53, v251, 53
	v_readlane_b32 s56, v251, 57
	s_cmp_lt_i32 s53, 3
	v_readlane_b32 s95, v251, 48
	v_readlane_b32 s97, v251, 49
	v_readlane_b32 s85, v251, 54
	v_readlane_b32 s54, v251, 59
	v_readlane_b32 s57, v251, 58
	v_readlane_b32 s55, v251, 56
	s_cbranch_scc1 .LBB0_680
	s_waitcnt vmcnt(0)
	v_cmp_eq_u32_e32 vcc, 0, v0
	s_waitcnt lgkmcnt(0)
	s_barrier
	s_and_saveexec_b64 s[0:1], vcc
	s_cbranch_execz .LBB0_679
	v_mov_b32_e32 v1, s79
	s_waitcnt vmcnt(0) expcnt(0) lgkmcnt(0)
	ds_read_b32 v3, v1
	ds_read_b32 v1, v1 offset:4
	s_waitcnt lgkmcnt(1)
	v_cmp_ne_u32_e32 vcc, 0, v3
	s_cbranch_vccnz .LBB0_647
	v_readlane_b32 s2, v251, 0
	v_readlane_b32 s3, v251, 1
	s_load_dwordx2 s[4:5], s[2:3], 0x4
	v_readlane_b32 s6, v251, 2
	v_readlane_b32 s7, v251, 3
	s_add_u32 s2, s6, 0x4200
	s_addc_u32 s3, s7, 0
	s_lshl_b32 s10, s55, 8
	s_waitcnt lgkmcnt(0)
	s_mul_i32 s11, s4, s97
	s_add_u32 s12, s6, 0x4400
	s_mov_b32 s9, 0
	s_mul_i32 s11, s11, s5
	s_addc_u32 s13, s7, 0
	v_mov_b32_e32 v2, 0
	s_branch .LBB0_636
